# attention rewritten: one unit computes both V halves (dv=128) per wave so QK^T and softmax are done once; bf16 MFMA operands, f32 accumulate, same as baseline; plus no setprio in GEMM loops
# speedup vs baseline: 1.0517x; 1.0517x over previous
.LBB0_771:
	s_lshr_b32 s44, s40, 8
	v_mov_b32_e32 v253, 0
	s_and_saveexec_b64 s[4:5], s[0:1]
	s_cbranch_execz .LBB0_775
	s_mov_b64 s[8:9], exec
	v_mbcnt_lo_u32_b32 v0, s8, 0
	v_mbcnt_hi_u32_b32 v0, s9, v0
	v_cmp_eq_u32_e32 vcc, 0, v0
	s_and_saveexec_b64 s[6:7], vcc
	s_cbranch_execz .LBB0_774
	s_lshl_b32 s2, s44, 8
	s_bcnt1_i32_b64 s8, s[8:9]
	v_mov_b32_e32 v2, s2
	v_mov_b32_e32 v3, s8
	global_atomic_add v2, v2, v3, s[82:83] sc0
.LBB0_774:
	s_or_b64 exec, exec, s[6:7]
	s_waitcnt vmcnt(0)
	v_readfirstlane_b32 s2, v2
	s_nop 1
	v_add_u32_e32 v253, s2, v0
.LBB0_775:
	s_or_b64 exec, exec, s[4:5]
	s_and_b32 s60, s40, 0xff
	s_and_b32 s61, s60, 63
	s_lshr_b32 s61, s61, 2
	s_sub_u32 s61, 15, s61
	s_lshr_b32 s62, s60, 6
	s_lshl_b32 s62, s62, 2
	s_and_b32 s63, s60, 3
	s_add_u32 s62, s62, s63
	s_lshl_b32 s62, s62, 3
	s_add_u32 s62, s62, s44
	s_and_b32 s63, s62, 1
	s_cmp_lg_u32 s63, 0
	s_cbranch_scc1 .Lat_unit_end
	s_lshr_b32 s64, s62, 4
	s_and_b32 s65, s62, 15
	s_lshl_b32 s45, s61, 2
	s_add_u32 s45, s45, 4
	s_sub_u32 s72, s45, 4
	v_lshrrev_b32_e32 v0, 6, v236
	s_nop 0
	v_readfirstlane_b32 s47, v0
	s_lshl_b32 s66, s64, 22
	s_lshr_b32 s67, s65, 1
	s_lshl_b32 s67, s67, 7
	s_add_u32 s48, s82, 0x9000000
	s_addc_u32 s49, s83, 0
	s_add_u32 s48, s48, s66
	s_addc_u32 s49, s49, 0
	s_add_u32 s48, s48, s67
	s_addc_u32 s49, s49, 0
	s_lshr_b32 s63, s65, 2
	s_lshl_b32 s63, s63, 8
	s_add_u32 s50, s82, 0xb000000
	s_addc_u32 s51, s83, 0
	s_add_u32 s50, s50, s66
	s_addc_u32 s51, s51, 0
	s_add_u32 s50, s50, s63
	s_addc_u32 s51, s51, 0
	s_lshl_b32 s63, s61, 8
	s_lshl_b32 s60, s47, 5
	s_add_u32 s63, s63, s60
	s_lshl_b32 s60, s63, 10
	s_add_u32 s54, s82, 0x7000000
	s_addc_u32 s55, s83, 0
	s_add_u32 s54, s54, s66
	s_addc_u32 s55, s55, 0
	s_add_u32 s54, s54, s60
	s_addc_u32 s55, s55, 0
	s_add_u32 s54, s54, s67
	s_addc_u32 s55, s55, 0
	s_lshl_b32 s60, s64, 12
	s_add_u32 s60, s60, s63
	s_lshl_b32 s60, s60, 11
	s_and_b32 s67, s65, 14
	s_lshl_b32 s67, s67, 7
	s_add_u32 s52, s82, 0x16000000
	s_addc_u32 s53, s83, 0
	s_add_u32 s52, s52, s60
	s_addc_u32 s53, s53, 0
	s_add_u32 s52, s52, s67
	s_addc_u32 s53, s53, 0
	v_and_b32_e32 v237, 63, v236
	v_lshrrev_b32_e32 v252, 5, v237
	v_and_b32_e32 v0, 31, v237
	s_lshl_b32 s60, s47, 4
	v_lshl_add_u32 v238, v237, 10, s60
	s_and_b32 s60, s47, 3
	s_lshl_b32 s60, s60, 14
	s_lshr_b32 s61, s47, 2
	s_lshl_b32 s61, s61, 6
	s_add_u32 s60, s60, s61
	v_lshrrev_b32_e32 v1, 2, v237
	v_lshlrev_b32_e32 v1, 10, v1
	v_and_b32_e32 v2, 3, v237
	v_lshl_or_b32 v1, v2, 4, v1
	v_add_u32_e32 v239, s60, v1
	v_lshlrev_b32_e32 v244, 10, v252
	v_lshl_or_b32 v244, v0, 4, v244
	v_bfe_u32 v1, v237, 4, 1
	v_lshlrev_b32_e32 v1, 5, v1
	v_lshl_or_b32 v1, v2, 3, v1
	v_bfe_u32 v2, v237, 2, 2
	v_lshl_or_b32 v2, v252, 2, v2
	v_lshl_or_b32 v1, v2, 6, v1
	v_add_u32_e32 v245, 24576, v1
	s_lshl_b32 s60, s47, 5
	v_add_u32_e32 v246, s60, v0
	s_lshl_b32 s60, s47, 8
	s_add_u32 s60, s60, 73728
	v_mov_b32_e32 v249, s60
	s_lshl_b32 s70, s47, 10
	s_add_u32 s71, s70, 24576
	s_mov_b64 s[74:75], s[48:49]
	s_mov_b64 s[76:77], s[50:51]
	s_mov_b32 s56, 0x4000
	s_mov_b32 s57, 0
	s_mov_b32 s58, 0x2000
	s_add_i32 m0, s57, s70
	s_nop 0
	global_load_lds_dwordx4 v238, s[74:75]
	s_add_u32 s74, s74, 0x10000
	s_addc_u32 s75, s75, 0
	s_lshl_b32 s60, s57, 1
	s_add_i32 s60, s60, s71
	s_mov_b32 m0, s60
	s_nop 0
	global_load_lds_dwordx4 v239, s[76:77]
	s_add_u32 s62, s76, 0x80
	s_addc_u32 s63, s77, 0
	s_add_i32 m0, s60, 0x2000
	s_nop 0
	global_load_lds_dwordx4 v239, s[62:63]
	s_add_u32 s76, s76, 0x10000
	s_addc_u32 s77, s77, 0
	s_add_i32 m0, s58, s70
	s_nop 0
	global_load_lds_dwordx4 v238, s[74:75]
	s_add_u32 s74, s74, 0x10000
	s_addc_u32 s75, s75, 0
	v_lshlrev_b32_e32 v1, 10, v0
	v_lshl_or_b32 v1, v252, 4, v1
	global_load_dwordx4 v[16:19], v1, s[54:55]
	global_load_dwordx4 v[20:23], v1, s[54:55] offset:32
	global_load_dwordx4 v[24:27], v1, s[54:55] offset:64
	global_load_dwordx4 v[28:31], v1, s[54:55] offset:96
	s_add_i32 m0, s56, s70
	s_nop 0
	global_load_lds_dwordx4 v238, s[74:75]
	s_add_u32 s74, s74, 0x10000
	s_addc_u32 s75, s75, 0
	v_mov_b32_e32 v248, 0
	v_mov_b32_e32 v247, 0
	v_mov_b32_e32 v160, 0
	v_mov_b32_e32 v161, 0
	v_mov_b32_e32 v162, 0
	v_mov_b32_e32 v163, 0
	v_mov_b32_e32 v164, 0
	v_mov_b32_e32 v165, 0
	v_mov_b32_e32 v166, 0
	v_mov_b32_e32 v167, 0
	v_mov_b32_e32 v168, 0
	v_mov_b32_e32 v169, 0
	v_mov_b32_e32 v170, 0
	v_mov_b32_e32 v171, 0
	v_mov_b32_e32 v172, 0
	v_mov_b32_e32 v173, 0
	v_mov_b32_e32 v174, 0
	v_mov_b32_e32 v175, 0
	v_mov_b32_e32 v32, 0
	v_mov_b32_e32 v33, 0
	v_mov_b32_e32 v34, 0
	v_mov_b32_e32 v35, 0
	v_mov_b32_e32 v36, 0
	v_mov_b32_e32 v37, 0
	v_mov_b32_e32 v38, 0
	v_mov_b32_e32 v39, 0
	v_mov_b32_e32 v40, 0
	v_mov_b32_e32 v41, 0
	v_mov_b32_e32 v42, 0
	v_mov_b32_e32 v43, 0
	v_mov_b32_e32 v44, 0
	v_mov_b32_e32 v45, 0
	v_mov_b32_e32 v46, 0
	v_mov_b32_e32 v47, 0
	v_mov_b32_e32 v48, 0
	v_mov_b32_e32 v49, 0
	v_mov_b32_e32 v50, 0
	v_mov_b32_e32 v51, 0
	v_mov_b32_e32 v52, 0
	v_mov_b32_e32 v53, 0
	v_mov_b32_e32 v54, 0
	v_mov_b32_e32 v55, 0
	v_mov_b32_e32 v56, 0
	v_mov_b32_e32 v57, 0
	v_mov_b32_e32 v58, 0
	v_mov_b32_e32 v59, 0
	v_mov_b32_e32 v60, 0
	v_mov_b32_e32 v61, 0
	v_mov_b32_e32 v62, 0
	v_mov_b32_e32 v63, 0
	v_mov_b32_e32 v64, 0
	v_mov_b32_e32 v65, 0
	v_mov_b32_e32 v66, 0
	v_mov_b32_e32 v67, 0
	v_mov_b32_e32 v68, 0
	v_mov_b32_e32 v69, 0
	v_mov_b32_e32 v70, 0
	v_mov_b32_e32 v71, 0
	v_mov_b32_e32 v72, 0
	v_mov_b32_e32 v73, 0
	v_mov_b32_e32 v74, 0
	v_mov_b32_e32 v75, 0
	v_mov_b32_e32 v76, 0
	v_mov_b32_e32 v77, 0
	v_mov_b32_e32 v78, 0
	v_mov_b32_e32 v79, 0
	v_mov_b32_e32 v80, 0
	v_mov_b32_e32 v81, 0
	v_mov_b32_e32 v82, 0
	v_mov_b32_e32 v83, 0
	v_mov_b32_e32 v84, 0
	v_mov_b32_e32 v85, 0
	v_mov_b32_e32 v86, 0
	v_mov_b32_e32 v87, 0
	v_mov_b32_e32 v88, 0
	v_mov_b32_e32 v89, 0
	v_mov_b32_e32 v90, 0
	v_mov_b32_e32 v91, 0
	v_mov_b32_e32 v92, 0
	v_mov_b32_e32 v93, 0
	v_mov_b32_e32 v94, 0
	v_mov_b32_e32 v95, 0
	s_mov_b32 s46, 0
	s_waitcnt vmcnt(8) lgkmcnt(0)
	s_barrier
	v_add_u32_e32 v250, s57, v244
	ds_read_b128 v[208:211], v250
	ds_read_b128 v[212:215], v250 offset:512
	ds_read_b128 v[216:219], v250 offset:2048
	ds_read_b128 v[220:223], v250 offset:2560
	ds_read_b128 v[224:227], v250 offset:4096
	ds_read_b128 v[228:231], v250 offset:4608
	ds_read_b128 v[232:235], v250 offset:6144
	ds_read_b128 v[240:243], v250 offset:6656
	s_waitcnt vmcnt(1) lgkmcnt(0)
	v_mfma_f32_32x32x16_bf16 v[96:111], v[208:211], v[16:19], v[160:175]
	v_mfma_f32_32x32x16_bf16 v[112:127], v[212:215], v[16:19], v[160:175]
	v_mfma_f32_32x32x16_bf16 v[96:111], v[216:219], v[20:23], v[96:111]
	v_mfma_f32_32x32x16_bf16 v[112:127], v[220:223], v[20:23], v[112:127]
	v_mfma_f32_32x32x16_bf16 v[96:111], v[224:227], v[24:27], v[96:111]
	v_mfma_f32_32x32x16_bf16 v[112:127], v[228:231], v[24:27], v[112:127]
	v_mfma_f32_32x32x16_bf16 v[96:111], v[232:235], v[28:31], v[96:111]
	v_mfma_f32_32x32x16_bf16 v[112:127], v[240:243], v[28:31], v[112:127]
	s_nop 7
	s_nop 7
	s_cmp_lt_u32 s46, s72
	s_cbranch_scc1 .Lat_nomask_236
	s_sub_u32 s60, s46, s72
	s_lshl_b32 s60, s60, 6
	v_lshl_add_u32 v0, v252, 2, s60
	v_sub_u32_e32 v0, v246, v0
	v_mov_b32_e32 v1, 0xff800000
	v_cmp_gt_i32_e64 s[60:61], 0, v0
	v_cmp_gt_i32_e64 s[62:63], 32, v0
	v_cmp_gt_i32_e64 s[64:65], 1, v0
	v_cmp_gt_i32_e64 s[66:67], 33, v0
	v_cndmask_b32_e64 v96, v96, v1, s[60:61]
	v_cmp_gt_i32_e64 s[60:61], 2, v0
	v_cndmask_b32_e64 v112, v112, v1, s[62:63]
	v_cmp_gt_i32_e64 s[62:63], 34, v0
	v_cndmask_b32_e64 v97, v97, v1, s[64:65]
	v_cmp_gt_i32_e64 s[64:65], 3, v0
	v_cndmask_b32_e64 v113, v113, v1, s[66:67]
	v_cmp_gt_i32_e64 s[66:67], 35, v0
	v_cndmask_b32_e64 v98, v98, v1, s[60:61]
	v_cmp_gt_i32_e64 s[60:61], 8, v0
	v_cndmask_b32_e64 v114, v114, v1, s[62:63]
	v_cmp_gt_i32_e64 s[62:63], 40, v0
	v_cndmask_b32_e64 v99, v99, v1, s[64:65]
	v_cmp_gt_i32_e64 s[64:65], 9, v0
	v_cndmask_b32_e64 v115, v115, v1, s[66:67]
	v_cmp_gt_i32_e64 s[66:67], 41, v0
	v_cndmask_b32_e64 v100, v100, v1, s[60:61]
	v_cmp_gt_i32_e64 s[60:61], 10, v0
	v_cndmask_b32_e64 v116, v116, v1, s[62:63]
	v_cmp_gt_i32_e64 s[62:63], 42, v0
	v_cndmask_b32_e64 v101, v101, v1, s[64:65]
	v_cmp_gt_i32_e64 s[64:65], 11, v0
	v_cndmask_b32_e64 v117, v117, v1, s[66:67]
	v_cmp_gt_i32_e64 s[66:67], 43, v0
	v_cndmask_b32_e64 v102, v102, v1, s[60:61]
	v_cmp_gt_i32_e64 s[60:61], 16, v0
	v_cndmask_b32_e64 v118, v118, v1, s[62:63]
	v_cmp_gt_i32_e64 s[62:63], 48, v0
	v_cndmask_b32_e64 v103, v103, v1, s[64:65]
	v_cmp_gt_i32_e64 s[64:65], 17, v0
	v_cndmask_b32_e64 v119, v119, v1, s[66:67]
	v_cmp_gt_i32_e64 s[66:67], 49, v0
	v_cndmask_b32_e64 v104, v104, v1, s[60:61]
	v_cmp_gt_i32_e64 s[60:61], 18, v0
	v_cndmask_b32_e64 v120, v120, v1, s[62:63]
	v_cmp_gt_i32_e64 s[62:63], 50, v0
	v_cndmask_b32_e64 v105, v105, v1, s[64:65]
	v_cmp_gt_i32_e64 s[64:65], 19, v0
	v_cndmask_b32_e64 v121, v121, v1, s[66:67]
	v_cmp_gt_i32_e64 s[66:67], 51, v0
	v_cndmask_b32_e64 v106, v106, v1, s[60:61]
	v_cmp_gt_i32_e64 s[60:61], 24, v0
	v_cndmask_b32_e64 v122, v122, v1, s[62:63]
	v_cmp_gt_i32_e64 s[62:63], 56, v0
	v_cndmask_b32_e64 v107, v107, v1, s[64:65]
	v_cmp_gt_i32_e64 s[64:65], 25, v0
	v_cndmask_b32_e64 v123, v123, v1, s[66:67]
	v_cmp_gt_i32_e64 s[66:67], 57, v0
	v_cndmask_b32_e64 v108, v108, v1, s[60:61]
	v_cmp_gt_i32_e64 s[60:61], 26, v0
	v_cndmask_b32_e64 v124, v124, v1, s[62:63]
	v_cmp_gt_i32_e64 s[62:63], 58, v0
	v_cndmask_b32_e64 v109, v109, v1, s[64:65]
	v_cmp_gt_i32_e64 s[64:65], 27, v0
	v_cndmask_b32_e64 v125, v125, v1, s[66:67]
	v_cmp_gt_i32_e64 s[66:67], 59, v0
	v_cndmask_b32_e64 v110, v110, v1, s[60:61]
	s_nop 1
	v_cndmask_b32_e64 v126, v126, v1, s[62:63]
	v_cndmask_b32_e64 v111, v111, v1, s[64:65]
	v_cndmask_b32_e64 v127, v127, v1, s[66:67]
.Lat_nomask_236:
	v_max3_f32 v2, v96, v97, v112
	v_max3_f32 v3, v98, v99, v113
	v_max3_f32 v2, v2, v114, v115
	v_max3_f32 v2, v2, v100, v101
	v_max3_f32 v3, v3, v102, v103
	v_max3_f32 v2, v2, v116, v117
	v_max3_f32 v3, v3, v118, v119
	v_max3_f32 v2, v2, v104, v105
	v_max3_f32 v3, v3, v106, v107
	v_max3_f32 v2, v2, v120, v121
	v_max3_f32 v3, v3, v122, v123
	v_max3_f32 v2, v2, v108, v109
	v_max3_f32 v3, v3, v110, v111
	v_max3_f32 v2, v2, v124, v125
	v_max3_f32 v3, v3, v126, v127
	v_max_f32_e32 v2, v2, v3
	v_mov_b32_e32 v3, v2
	s_nop 1
	v_permlane32_swap_b32_e32 v2, v3
	v_max_f32_e32 v2, v2, v3
	v_mov_b32_e32 v4, v2
	s_mov_b64 s[68:69], 0
	v_add_f32_e32 v248, v248, v4
	v_sub_f32_e32 v96, v96, v4
	v_sub_f32_e32 v97, v97, v4
	v_sub_f32_e32 v98, v98, v4
	v_sub_f32_e32 v99, v99, v4
	v_sub_f32_e32 v100, v100, v4
	v_sub_f32_e32 v101, v101, v4
	v_sub_f32_e32 v102, v102, v4
	v_sub_f32_e32 v103, v103, v4
	v_sub_f32_e32 v104, v104, v4
	v_sub_f32_e32 v105, v105, v4
	v_sub_f32_e32 v106, v106, v4
	v_sub_f32_e32 v107, v107, v4
	v_sub_f32_e32 v108, v108, v4
	v_sub_f32_e32 v109, v109, v4
	v_sub_f32_e32 v110, v110, v4
	v_sub_f32_e32 v111, v111, v4
	v_sub_f32_e32 v112, v112, v4
	v_sub_f32_e32 v113, v113, v4
	v_sub_f32_e32 v114, v114, v4
	v_sub_f32_e32 v115, v115, v4
	v_sub_f32_e32 v116, v116, v4
	v_sub_f32_e32 v117, v117, v4
	v_sub_f32_e32 v118, v118, v4
	v_sub_f32_e32 v119, v119, v4
	v_sub_f32_e32 v120, v120, v4
	v_sub_f32_e32 v121, v121, v4
	v_sub_f32_e32 v122, v122, v4
	v_sub_f32_e32 v123, v123, v4
	v_sub_f32_e32 v124, v124, v4
	v_sub_f32_e32 v125, v125, v4
	v_sub_f32_e32 v126, v126, v4
	v_sub_f32_e32 v127, v127, v4
	v_xor_b32_e32 v5, 0x80000000, v248
	v_mov_b32_e32 v160, v5
	v_mov_b32_e32 v161, v5
	v_mov_b32_e32 v162, v5
	v_mov_b32_e32 v163, v5
	v_mov_b32_e32 v164, v5
	v_mov_b32_e32 v165, v5
	v_mov_b32_e32 v166, v5
	v_mov_b32_e32 v167, v5
	v_mov_b32_e32 v168, v5
	v_mov_b32_e32 v169, v5
	v_mov_b32_e32 v170, v5
	v_mov_b32_e32 v171, v5
	v_mov_b32_e32 v172, v5
	v_mov_b32_e32 v173, v5
	v_mov_b32_e32 v174, v5
	v_mov_b32_e32 v175, v5
	v_exp_f32_e32 v96, v96
	v_exp_f32_e32 v97, v97
	v_exp_f32_e32 v98, v98
	v_exp_f32_e32 v99, v99
	v_exp_f32_e32 v100, v100
	v_exp_f32_e32 v101, v101
	v_exp_f32_e32 v102, v102
	v_exp_f32_e32 v103, v103
	v_exp_f32_e32 v104, v104
	v_exp_f32_e32 v105, v105
	v_exp_f32_e32 v106, v106
	v_exp_f32_e32 v107, v107
	v_exp_f32_e32 v108, v108
	v_exp_f32_e32 v109, v109
	v_exp_f32_e32 v110, v110
	v_exp_f32_e32 v111, v111
	v_exp_f32_e32 v112, v112
	v_exp_f32_e32 v113, v113
	v_exp_f32_e32 v114, v114
	v_exp_f32_e32 v115, v115
	v_exp_f32_e32 v116, v116
	v_exp_f32_e32 v117, v117
	v_exp_f32_e32 v118, v118
	v_exp_f32_e32 v119, v119
	v_exp_f32_e32 v120, v120
	v_exp_f32_e32 v121, v121
	v_exp_f32_e32 v122, v122
	v_exp_f32_e32 v123, v123
	v_exp_f32_e32 v124, v124
	v_exp_f32_e32 v125, v125
	v_exp_f32_e32 v126, v126
	v_exp_f32_e32 v127, v127
	s_waitcnt vmcnt(0) lgkmcnt(0)
	s_barrier
	s_add_i32 m0, s57, s70
	s_nop 0
	global_load_lds_dwordx4 v238, s[74:75]
	s_add_u32 s74, s74, 0x10000
	s_addc_u32 s75, s75, 0
	s_lshl_b32 s60, s58, 1
	s_add_i32 s60, s60, s71
	s_mov_b32 m0, s60
	s_nop 0
	global_load_lds_dwordx4 v239, s[76:77]
	s_add_u32 s62, s76, 0x80
	s_addc_u32 s63, s77, 0
	s_add_i32 m0, s60, 0x2000
	s_nop 0
	global_load_lds_dwordx4 v239, s[62:63]
	s_add_u32 s76, s76, 0x10000
	s_addc_u32 s77, s77, 0
	s_mov_b32 s67, s56
	s_mov_b32 s56, s57
	s_mov_b32 s57, s58
	s_mov_b32 s58, s67
	v_add_u32_e32 v250, s57, v244
	ds_read_b128 v[208:211], v250
	ds_read_b128 v[212:215], v250 offset:512
	ds_read_b128 v[216:219], v250 offset:2048
	ds_read_b128 v[220:223], v250 offset:2560
	ds_read_b128 v[224:227], v250 offset:4096
	ds_read_b128 v[228:231], v250 offset:4608
	ds_read_b128 v[232:235], v250 offset:6144
	ds_read_b128 v[240:243], v250 offset:6656
	s_mov_b32 s46, 1
	s_waitcnt vmcnt(3) lgkmcnt(0)
	s_barrier
.Lat_loop:
	s_cmp_ge_u32 s46, s45
	s_cbranch_scc1 .Lat_drain
	v_mov_b32_e32 v251, 0
	v_mfma_f32_32x32x16_bf16 v[128:143], v[208:211], v[16:19], v[160:175]
	v_add_f32_e32 v251, v251, v96
	v_add_f32_e32 v251, v251, v97
	v_add_f32_e32 v251, v251, v98
	v_add_f32_e32 v251, v251, v99
	v_cvt_pk_bf16_f32 v176, v96, v97
	v_cvt_pk_bf16_f32 v177, v98, v99
	v_mfma_f32_32x32x16_bf16 v[144:159], v[212:215], v[16:19], v[160:175]
	v_add_f32_e32 v251, v251, v100
	v_add_f32_e32 v251, v251, v101
	v_add_f32_e32 v251, v251, v102
	v_add_f32_e32 v251, v251, v103
	v_cvt_pk_bf16_f32 v178, v100, v101
	v_cvt_pk_bf16_f32 v179, v102, v103
	v_mfma_f32_32x32x16_bf16 v[128:143], v[216:219], v[20:23], v[128:143]
	v_add_f32_e32 v251, v251, v104
	v_add_f32_e32 v251, v251, v105
	v_add_f32_e32 v251, v251, v106
	v_add_f32_e32 v251, v251, v107
	v_cvt_pk_bf16_f32 v180, v104, v105
	v_cvt_pk_bf16_f32 v181, v106, v107
	v_mfma_f32_32x32x16_bf16 v[144:159], v[220:223], v[20:23], v[144:159]
	v_add_f32_e32 v251, v251, v108
	v_add_f32_e32 v251, v251, v109
	v_add_f32_e32 v251, v251, v110
	v_add_f32_e32 v251, v251, v111
	v_cvt_pk_bf16_f32 v182, v108, v109
	v_cvt_pk_bf16_f32 v183, v110, v111
	v_mfma_f32_32x32x16_bf16 v[128:143], v[224:227], v[24:27], v[128:143]
	v_add_f32_e32 v251, v251, v112
	v_add_f32_e32 v251, v251, v113
	v_add_f32_e32 v251, v251, v114
	v_add_f32_e32 v251, v251, v115
	v_cvt_pk_bf16_f32 v184, v112, v113
	v_cvt_pk_bf16_f32 v185, v114, v115
	v_mfma_f32_32x32x16_bf16 v[144:159], v[228:231], v[24:27], v[144:159]
	v_add_f32_e32 v251, v251, v116
	v_add_f32_e32 v251, v251, v117
	v_add_f32_e32 v251, v251, v118
	v_add_f32_e32 v251, v251, v119
	v_cvt_pk_bf16_f32 v186, v116, v117
	v_cvt_pk_bf16_f32 v187, v118, v119
	v_mfma_f32_32x32x16_bf16 v[128:143], v[232:235], v[28:31], v[128:143]
	v_add_f32_e32 v251, v251, v120
	v_add_f32_e32 v251, v251, v121
	v_add_f32_e32 v251, v251, v122
	v_add_f32_e32 v251, v251, v123
	v_cvt_pk_bf16_f32 v188, v120, v121
	v_cvt_pk_bf16_f32 v189, v122, v123
	v_mfma_f32_32x32x16_bf16 v[144:159], v[240:243], v[28:31], v[144:159]
	v_add_f32_e32 v251, v251, v124
	v_add_f32_e32 v251, v251, v125
	v_add_f32_e32 v251, v251, v126
	v_add_f32_e32 v251, v251, v127
	v_cvt_pk_bf16_f32 v190, v124, v125
	v_cvt_pk_bf16_f32 v191, v126, v127
	v_add_f32_e32 v247, v247, v251
	s_add_i32 m0, s57, s70
	s_nop 0
	global_load_lds_dwordx4 v238, s[74:75]
	s_add_u32 s74, s74, 0x10000
	s_addc_u32 s75, s75, 0
	s_lshl_b32 s60, s58, 1
	s_add_i32 s60, s60, s71
	s_mov_b32 m0, s60
	s_nop 0
	global_load_lds_dwordx4 v239, s[76:77]
	s_add_u32 s62, s76, 0x80
	s_addc_u32 s63, s77, 0
	s_add_i32 m0, s60, 0x2000
	s_nop 0
	global_load_lds_dwordx4 v239, s[62:63]
	s_add_u32 s76, s76, 0x10000
	s_addc_u32 s77, s77, 0
	s_lshl_b32 s60, s56, 1
	v_add_u32_e32 v250, s60, v245
	ds_read_b64_tr_b16 v[192:193], v250 offset:0
	ds_read_b64_tr_b16 v[194:195], v250 offset:512
	ds_read_b64_tr_b16 v[196:197], v250 offset:4096
	ds_read_b64_tr_b16 v[198:199], v250 offset:4608
	s_nop 7
	s_cmp_lt_u32 s46, s72
	s_cbranch_scc1 .Lat_nomask_533
	s_sub_u32 s60, s46, s72
	s_lshl_b32 s60, s60, 6
	v_lshl_add_u32 v0, v252, 2, s60
	v_sub_u32_e32 v0, v246, v0
	v_mov_b32_e32 v1, 0xff800000
	v_cmp_gt_i32_e64 s[60:61], 0, v0
	v_cmp_gt_i32_e64 s[62:63], 32, v0
	v_cmp_gt_i32_e64 s[64:65], 1, v0
	v_cmp_gt_i32_e64 s[66:67], 33, v0
	v_cndmask_b32_e64 v128, v128, v1, s[60:61]
	v_cmp_gt_i32_e64 s[60:61], 2, v0
	v_cndmask_b32_e64 v144, v144, v1, s[62:63]
	v_cmp_gt_i32_e64 s[62:63], 34, v0
	v_cndmask_b32_e64 v129, v129, v1, s[64:65]
	v_cmp_gt_i32_e64 s[64:65], 3, v0
	v_cndmask_b32_e64 v145, v145, v1, s[66:67]
	v_cmp_gt_i32_e64 s[66:67], 35, v0
	v_cndmask_b32_e64 v130, v130, v1, s[60:61]
	v_cmp_gt_i32_e64 s[60:61], 8, v0
	v_cndmask_b32_e64 v146, v146, v1, s[62:63]
	v_cmp_gt_i32_e64 s[62:63], 40, v0
	v_cndmask_b32_e64 v131, v131, v1, s[64:65]
	v_cmp_gt_i32_e64 s[64:65], 9, v0
	v_cndmask_b32_e64 v147, v147, v1, s[66:67]
	v_cmp_gt_i32_e64 s[66:67], 41, v0
	v_cndmask_b32_e64 v132, v132, v1, s[60:61]
	v_cmp_gt_i32_e64 s[60:61], 10, v0
	v_cndmask_b32_e64 v148, v148, v1, s[62:63]
	v_cmp_gt_i32_e64 s[62:63], 42, v0
	v_cndmask_b32_e64 v133, v133, v1, s[64:65]
	v_cmp_gt_i32_e64 s[64:65], 11, v0
	v_cndmask_b32_e64 v149, v149, v1, s[66:67]
	v_cmp_gt_i32_e64 s[66:67], 43, v0
	v_cndmask_b32_e64 v134, v134, v1, s[60:61]
	v_cmp_gt_i32_e64 s[60:61], 16, v0
	v_cndmask_b32_e64 v150, v150, v1, s[62:63]
	v_cmp_gt_i32_e64 s[62:63], 48, v0
	v_cndmask_b32_e64 v135, v135, v1, s[64:65]
	v_cmp_gt_i32_e64 s[64:65], 17, v0
	v_cndmask_b32_e64 v151, v151, v1, s[66:67]
	v_cmp_gt_i32_e64 s[66:67], 49, v0
	v_cndmask_b32_e64 v136, v136, v1, s[60:61]
	v_cmp_gt_i32_e64 s[60:61], 18, v0
	v_cndmask_b32_e64 v152, v152, v1, s[62:63]
	v_cmp_gt_i32_e64 s[62:63], 50, v0
	v_cndmask_b32_e64 v137, v137, v1, s[64:65]
	v_cmp_gt_i32_e64 s[64:65], 19, v0
	v_cndmask_b32_e64 v153, v153, v1, s[66:67]
	v_cmp_gt_i32_e64 s[66:67], 51, v0
	v_cndmask_b32_e64 v138, v138, v1, s[60:61]
	v_cmp_gt_i32_e64 s[60:61], 24, v0
	v_cndmask_b32_e64 v154, v154, v1, s[62:63]
	v_cmp_gt_i32_e64 s[62:63], 56, v0
	v_cndmask_b32_e64 v139, v139, v1, s[64:65]
	v_cmp_gt_i32_e64 s[64:65], 25, v0
	v_cndmask_b32_e64 v155, v155, v1, s[66:67]
	v_cmp_gt_i32_e64 s[66:67], 57, v0
	v_cndmask_b32_e64 v140, v140, v1, s[60:61]
	v_cmp_gt_i32_e64 s[60:61], 26, v0
	v_cndmask_b32_e64 v156, v156, v1, s[62:63]
	v_cmp_gt_i32_e64 s[62:63], 58, v0
	v_cndmask_b32_e64 v141, v141, v1, s[64:65]
	v_cmp_gt_i32_e64 s[64:65], 27, v0
	v_cndmask_b32_e64 v157, v157, v1, s[66:67]
	v_cmp_gt_i32_e64 s[66:67], 59, v0
	v_cndmask_b32_e64 v142, v142, v1, s[60:61]
	s_nop 1
	v_cndmask_b32_e64 v158, v158, v1, s[62:63]
	v_cndmask_b32_e64 v143, v143, v1, s[64:65]
	v_cndmask_b32_e64 v159, v159, v1, s[66:67]
.Lat_nomask_533:
	v_max3_f32 v2, v128, v129, v144
	v_max3_f32 v3, v130, v131, v145
	v_max3_f32 v2, v2, v146, v147
	v_max3_f32 v2, v2, v132, v133
	v_max3_f32 v3, v3, v134, v135
	v_max3_f32 v2, v2, v148, v149
	v_max3_f32 v3, v3, v150, v151
	v_max3_f32 v2, v2, v136, v137
	v_max3_f32 v3, v3, v138, v139
	v_max3_f32 v2, v2, v152, v153
	v_max3_f32 v3, v3, v154, v155
	v_max3_f32 v2, v2, v140, v141
	v_max3_f32 v3, v3, v142, v143
	v_max3_f32 v2, v2, v156, v157
	v_max3_f32 v3, v3, v158, v159
	v_max_f32_e32 v2, v2, v3
	v_mov_b32_e32 v3, v2
	s_nop 1
	v_permlane32_swap_b32_e32 v2, v3
	v_max_f32_e32 v2, v2, v3
	v_mov_b32_e32 v5, 0x41400000
	v_cmp_gt_f32_e32 vcc, v2, v5
	s_mov_b64 s[68:69], vcc
	s_cmp_lg_u64 vcc, 0
	s_cbranch_scc0 .Lat_noresc_533
	v_max_f32_e32 v4, 0, v2
	v_add_f32_e32 v248, v248, v4
	v_sub_f32_e32 v128, v128, v4
	v_sub_f32_e32 v129, v129, v4
	v_sub_f32_e32 v130, v130, v4
	v_sub_f32_e32 v131, v131, v4
	v_sub_f32_e32 v132, v132, v4
	v_sub_f32_e32 v133, v133, v4
	v_sub_f32_e32 v134, v134, v4
	v_sub_f32_e32 v135, v135, v4
	v_sub_f32_e32 v136, v136, v4
	v_sub_f32_e32 v137, v137, v4
	v_sub_f32_e32 v138, v138, v4
	v_sub_f32_e32 v139, v139, v4
	v_sub_f32_e32 v140, v140, v4
	v_sub_f32_e32 v141, v141, v4
	v_sub_f32_e32 v142, v142, v4
	v_sub_f32_e32 v143, v143, v4
	v_sub_f32_e32 v144, v144, v4
	v_sub_f32_e32 v145, v145, v4
	v_sub_f32_e32 v146, v146, v4
	v_sub_f32_e32 v147, v147, v4
	v_sub_f32_e32 v148, v148, v4
	v_sub_f32_e32 v149, v149, v4
	v_sub_f32_e32 v150, v150, v4
	v_sub_f32_e32 v151, v151, v4
	v_sub_f32_e32 v152, v152, v4
	v_sub_f32_e32 v153, v153, v4
	v_sub_f32_e32 v154, v154, v4
	v_sub_f32_e32 v155, v155, v4
	v_sub_f32_e32 v156, v156, v4
	v_sub_f32_e32 v157, v157, v4
	v_sub_f32_e32 v158, v158, v4
	v_sub_f32_e32 v159, v159, v4
	v_xor_b32_e32 v5, 0x80000000, v248
	v_mov_b32_e32 v160, v5
	v_mov_b32_e32 v161, v5
	v_mov_b32_e32 v162, v5
	v_mov_b32_e32 v163, v5
	v_mov_b32_e32 v164, v5
	v_mov_b32_e32 v165, v5
	v_mov_b32_e32 v166, v5
	v_mov_b32_e32 v167, v5
	v_mov_b32_e32 v168, v5
	v_mov_b32_e32 v169, v5
	v_mov_b32_e32 v170, v5
	v_mov_b32_e32 v171, v5
	v_mov_b32_e32 v172, v5
	v_mov_b32_e32 v173, v5
	v_mov_b32_e32 v174, v5
	v_mov_b32_e32 v175, v5
	v_xor_b32_e32 v6, 0x80000000, v4
	v_exp_f32_e32 v6, v6
	s_nop 0
	v_mul_f32_e32 v247, v247, v6
	v_and_b32_e32 v7, 31, v237
	v_lshl_add_u32 v7, v7, 2, v249
	v_cmp_eq_u32_e32 vcc, 0, v252
	s_and_saveexec_b64 s[60:61], vcc
	ds_write_b32 v7, v6
	s_or_b64 exec, exec, s[60:61]
.Lat_noresc_533:
	ds_read_b64_tr_b16 v[200:201], v250 offset:8192
	ds_read_b64_tr_b16 v[202:203], v250 offset:8704
	s_waitcnt lgkmcnt(4)
	v_mfma_f32_32x32x16_bf16 v[32:47], v[176:179], v[192:195], v[32:47]
	v_exp_f32_e32 v128, v128
	v_exp_f32_e32 v129, v129
	ds_read_b64_tr_b16 v[204:205], v250 offset:12288
	ds_read_b64_tr_b16 v[206:207], v250 offset:12800
	s_waitcnt lgkmcnt(4)
	v_mfma_f32_32x32x16_bf16 v[48:63], v[176:179], v[196:199], v[48:63]
	v_exp_f32_e32 v130, v130
	v_exp_f32_e32 v131, v131
	ds_read_b64_tr_b16 v[192:193], v250 offset:1024
	ds_read_b64_tr_b16 v[194:195], v250 offset:1536
	s_waitcnt lgkmcnt(4)
	v_mfma_f32_32x32x16_bf16 v[64:79], v[176:179], v[200:203], v[64:79]
	v_exp_f32_e32 v132, v132
	v_exp_f32_e32 v133, v133
	ds_read_b64_tr_b16 v[196:197], v250 offset:5120
	ds_read_b64_tr_b16 v[198:199], v250 offset:5632
	s_waitcnt lgkmcnt(4)
	v_mfma_f32_32x32x16_bf16 v[80:95], v[176:179], v[204:207], v[80:95]
	v_exp_f32_e32 v134, v134
	v_exp_f32_e32 v135, v135
	v_add_u32_e32 v3, s58, v244
	ds_read_b64_tr_b16 v[200:201], v250 offset:9216
	ds_read_b64_tr_b16 v[202:203], v250 offset:9728
	s_waitcnt lgkmcnt(4)
	v_mfma_f32_32x32x16_bf16 v[32:47], v[180:183], v[192:195], v[32:47]
	v_exp_f32_e32 v136, v136
	v_exp_f32_e32 v137, v137
	ds_read_b128 v[208:211], v3
	ds_read_b64_tr_b16 v[204:205], v250 offset:13312
	ds_read_b64_tr_b16 v[206:207], v250 offset:13824
	s_waitcnt lgkmcnt(5)
	v_mfma_f32_32x32x16_bf16 v[48:63], v[180:183], v[196:199], v[48:63]
	v_exp_f32_e32 v138, v138
	v_exp_f32_e32 v139, v139
	ds_read_b128 v[212:215], v3 offset:512
	ds_read_b64_tr_b16 v[192:193], v250 offset:2048
	ds_read_b64_tr_b16 v[194:195], v250 offset:2560
	s_waitcnt lgkmcnt(6)
	v_mfma_f32_32x32x16_bf16 v[64:79], v[180:183], v[200:203], v[64:79]
	v_exp_f32_e32 v140, v140
	v_exp_f32_e32 v141, v141
	ds_read_b128 v[216:219], v3 offset:2048
	ds_read_b64_tr_b16 v[196:197], v250 offset:6144
	ds_read_b64_tr_b16 v[198:199], v250 offset:6656
	s_waitcnt lgkmcnt(6)
	v_mfma_f32_32x32x16_bf16 v[80:95], v[180:183], v[204:207], v[80:95]
	v_exp_f32_e32 v142, v142
	v_exp_f32_e32 v143, v143
	ds_read_b128 v[220:223], v3 offset:2560
	ds_read_b64_tr_b16 v[200:201], v250 offset:10240
	ds_read_b64_tr_b16 v[202:203], v250 offset:10752
	s_waitcnt lgkmcnt(6)
	v_mfma_f32_32x32x16_bf16 v[32:47], v[184:187], v[192:195], v[32:47]
	v_exp_f32_e32 v144, v144
	v_exp_f32_e32 v145, v145
	ds_read_b128 v[224:227], v3 offset:4096
	ds_read_b64_tr_b16 v[204:205], v250 offset:14336
	ds_read_b64_tr_b16 v[206:207], v250 offset:14848
	s_waitcnt lgkmcnt(6)
	v_mfma_f32_32x32x16_bf16 v[48:63], v[184:187], v[196:199], v[48:63]
	v_exp_f32_e32 v146, v146
	v_exp_f32_e32 v147, v147
	ds_read_b128 v[228:231], v3 offset:4608
	ds_read_b64_tr_b16 v[192:193], v250 offset:3072
	ds_read_b64_tr_b16 v[194:195], v250 offset:3584
	s_waitcnt lgkmcnt(6)
	v_mfma_f32_32x32x16_bf16 v[64:79], v[184:187], v[200:203], v[64:79]
	v_exp_f32_e32 v148, v148
	v_exp_f32_e32 v149, v149
	ds_read_b128 v[232:235], v3 offset:6144
	ds_read_b64_tr_b16 v[196:197], v250 offset:7168
	ds_read_b64_tr_b16 v[198:199], v250 offset:7680
	s_waitcnt lgkmcnt(6)
	v_mfma_f32_32x32x16_bf16 v[80:95], v[184:187], v[204:207], v[80:95]
	v_exp_f32_e32 v150, v150
	v_exp_f32_e32 v151, v151
	ds_read_b128 v[240:243], v3 offset:6656
	ds_read_b64_tr_b16 v[200:201], v250 offset:11264
	ds_read_b64_tr_b16 v[202:203], v250 offset:11776
	s_waitcnt lgkmcnt(6)
	v_mfma_f32_32x32x16_bf16 v[32:47], v[188:191], v[192:195], v[32:47]
	v_exp_f32_e32 v152, v152
	v_exp_f32_e32 v153, v153
	ds_read_b64_tr_b16 v[204:205], v250 offset:15360
	ds_read_b64_tr_b16 v[206:207], v250 offset:15872
	s_waitcnt lgkmcnt(5)
	v_mfma_f32_32x32x16_bf16 v[48:63], v[188:191], v[196:199], v[48:63]
	v_exp_f32_e32 v154, v154
	v_exp_f32_e32 v155, v155
	s_waitcnt lgkmcnt(2)
	v_mfma_f32_32x32x16_bf16 v[64:79], v[188:191], v[200:203], v[64:79]
	v_exp_f32_e32 v156, v156
	v_exp_f32_e32 v157, v157
	s_waitcnt lgkmcnt(0)
	v_mfma_f32_32x32x16_bf16 v[80:95], v[188:191], v[204:207], v[80:95]
	v_exp_f32_e32 v158, v158
	v_exp_f32_e32 v159, v159
	s_waitcnt vmcnt(3) lgkmcnt(0)
	s_barrier
	s_cmp_lg_u64 s[68:69], 0
	s_cbranch_scc0 .Lat_norescO_449
	v_lshl_add_u32 v250, v252, 4, v249
	ds_read_b128 v[0:3], v250 offset:0
	ds_read_b128 v[4:7], v250 offset:32
	ds_read_b128 v[8:11], v250 offset:64
	ds_read_b128 v[12:15], v250 offset:96
	s_nop 7
	s_nop 7
	s_waitcnt lgkmcnt(0)
	v_mul_f32_e32 v32, v32, v0
	v_mul_f32_e32 v33, v33, v1
	v_mul_f32_e32 v34, v34, v2
	v_mul_f32_e32 v35, v35, v3
	v_mul_f32_e32 v36, v36, v4
	v_mul_f32_e32 v37, v37, v5
	v_mul_f32_e32 v38, v38, v6
	v_mul_f32_e32 v39, v39, v7
	v_mul_f32_e32 v40, v40, v8
	v_mul_f32_e32 v41, v41, v9
	v_mul_f32_e32 v42, v42, v10
	v_mul_f32_e32 v43, v43, v11
	v_mul_f32_e32 v44, v44, v12
	v_mul_f32_e32 v45, v45, v13
	v_mul_f32_e32 v46, v46, v14
	v_mul_f32_e32 v47, v47, v15
	v_mul_f32_e32 v48, v48, v0
	v_mul_f32_e32 v49, v49, v1
	v_mul_f32_e32 v50, v50, v2
	v_mul_f32_e32 v51, v51, v3
	v_mul_f32_e32 v52, v52, v4
	v_mul_f32_e32 v53, v53, v5
	v_mul_f32_e32 v54, v54, v6
	v_mul_f32_e32 v55, v55, v7
	v_mul_f32_e32 v56, v56, v8
	v_mul_f32_e32 v57, v57, v9
	v_mul_f32_e32 v58, v58, v10
	v_mul_f32_e32 v59, v59, v11
	v_mul_f32_e32 v60, v60, v12
	v_mul_f32_e32 v61, v61, v13
	v_mul_f32_e32 v62, v62, v14
	v_mul_f32_e32 v63, v63, v15
	v_mul_f32_e32 v64, v64, v0
	v_mul_f32_e32 v65, v65, v1
	v_mul_f32_e32 v66, v66, v2
	v_mul_f32_e32 v67, v67, v3
	v_mul_f32_e32 v68, v68, v4
	v_mul_f32_e32 v69, v69, v5
	v_mul_f32_e32 v70, v70, v6
	v_mul_f32_e32 v71, v71, v7
	v_mul_f32_e32 v72, v72, v8
	v_mul_f32_e32 v73, v73, v9
	v_mul_f32_e32 v74, v74, v10
	v_mul_f32_e32 v75, v75, v11
	v_mul_f32_e32 v76, v76, v12
	v_mul_f32_e32 v77, v77, v13
	v_mul_f32_e32 v78, v78, v14
	v_mul_f32_e32 v79, v79, v15
	v_mul_f32_e32 v80, v80, v0
	v_mul_f32_e32 v81, v81, v1
	v_mul_f32_e32 v82, v82, v2
	v_mul_f32_e32 v83, v83, v3
	v_mul_f32_e32 v84, v84, v4
	v_mul_f32_e32 v85, v85, v5
	v_mul_f32_e32 v86, v86, v6
	v_mul_f32_e32 v87, v87, v7
	v_mul_f32_e32 v88, v88, v8
	v_mul_f32_e32 v89, v89, v9
	v_mul_f32_e32 v90, v90, v10
	v_mul_f32_e32 v91, v91, v11
	v_mul_f32_e32 v92, v92, v12
	v_mul_f32_e32 v93, v93, v13
	v_mul_f32_e32 v94, v94, v14
	v_mul_f32_e32 v95, v95, v15
.Lat_norescO_449:
	s_mov_b32 s67, s56
	s_mov_b32 s56, s57
	s_mov_b32 s57, s58
	s_mov_b32 s58, s67
	s_add_u32 s46, s46, 1
	s_cmp_ge_u32 s46, s45
	s_cbranch_scc1 .Lat_drain
	v_mov_b32_e32 v251, 0
	v_mfma_f32_32x32x16_bf16 v[96:111], v[208:211], v[16:19], v[160:175]
	v_add_f32_e32 v251, v251, v128
	v_add_f32_e32 v251, v251, v129
	v_add_f32_e32 v251, v251, v130
	v_add_f32_e32 v251, v251, v131
	v_cvt_pk_bf16_f32 v176, v128, v129
	v_cvt_pk_bf16_f32 v177, v130, v131
	v_mfma_f32_32x32x16_bf16 v[112:127], v[212:215], v[16:19], v[160:175]
	v_add_f32_e32 v251, v251, v132
	v_add_f32_e32 v251, v251, v133
	v_add_f32_e32 v251, v251, v134
	v_add_f32_e32 v251, v251, v135
	v_cvt_pk_bf16_f32 v178, v132, v133
	v_cvt_pk_bf16_f32 v179, v134, v135
	v_mfma_f32_32x32x16_bf16 v[96:111], v[216:219], v[20:23], v[96:111]
	v_add_f32_e32 v251, v251, v136
	v_add_f32_e32 v251, v251, v137
	v_add_f32_e32 v251, v251, v138
	v_add_f32_e32 v251, v251, v139
	v_cvt_pk_bf16_f32 v180, v136, v137
	v_cvt_pk_bf16_f32 v181, v138, v139
	v_mfma_f32_32x32x16_bf16 v[112:127], v[220:223], v[20:23], v[112:127]
	v_add_f32_e32 v251, v251, v140
	v_add_f32_e32 v251, v251, v141
	v_add_f32_e32 v251, v251, v142
	v_add_f32_e32 v251, v251, v143
	v_cvt_pk_bf16_f32 v182, v140, v141
	v_cvt_pk_bf16_f32 v183, v142, v143
	v_mfma_f32_32x32x16_bf16 v[96:111], v[224:227], v[24:27], v[96:111]
	v_add_f32_e32 v251, v251, v144
	v_add_f32_e32 v251, v251, v145
	v_add_f32_e32 v251, v251, v146
	v_add_f32_e32 v251, v251, v147
	v_cvt_pk_bf16_f32 v184, v144, v145
	v_cvt_pk_bf16_f32 v185, v146, v147
	v_mfma_f32_32x32x16_bf16 v[112:127], v[228:231], v[24:27], v[112:127]
	v_add_f32_e32 v251, v251, v148
	v_add_f32_e32 v251, v251, v149
	v_add_f32_e32 v251, v251, v150
	v_add_f32_e32 v251, v251, v151
	v_cvt_pk_bf16_f32 v186, v148, v149
	v_cvt_pk_bf16_f32 v187, v150, v151
	v_mfma_f32_32x32x16_bf16 v[96:111], v[232:235], v[28:31], v[96:111]
	v_add_f32_e32 v251, v251, v152
	v_add_f32_e32 v251, v251, v153
	v_add_f32_e32 v251, v251, v154
	v_add_f32_e32 v251, v251, v155
	v_cvt_pk_bf16_f32 v188, v152, v153
	v_cvt_pk_bf16_f32 v189, v154, v155
	v_mfma_f32_32x32x16_bf16 v[112:127], v[240:243], v[28:31], v[112:127]
	v_add_f32_e32 v251, v251, v156
	v_add_f32_e32 v251, v251, v157
	v_add_f32_e32 v251, v251, v158
	v_add_f32_e32 v251, v251, v159
	v_cvt_pk_bf16_f32 v190, v156, v157
	v_cvt_pk_bf16_f32 v191, v158, v159
	v_add_f32_e32 v247, v247, v251
	s_add_i32 m0, s57, s70
	s_nop 0
	global_load_lds_dwordx4 v238, s[74:75]
	s_add_u32 s74, s74, 0x10000
	s_addc_u32 s75, s75, 0
	s_lshl_b32 s60, s58, 1
	s_add_i32 s60, s60, s71
	s_mov_b32 m0, s60
	s_nop 0
	global_load_lds_dwordx4 v239, s[76:77]
	s_add_u32 s62, s76, 0x80
	s_addc_u32 s63, s77, 0
	s_add_i32 m0, s60, 0x2000
	s_nop 0
	global_load_lds_dwordx4 v239, s[62:63]
	s_add_u32 s76, s76, 0x10000
	s_addc_u32 s77, s77, 0
	s_lshl_b32 s60, s56, 1
	v_add_u32_e32 v250, s60, v245
	ds_read_b64_tr_b16 v[192:193], v250 offset:0
	ds_read_b64_tr_b16 v[194:195], v250 offset:512
	ds_read_b64_tr_b16 v[196:197], v250 offset:4096
	ds_read_b64_tr_b16 v[198:199], v250 offset:4608
	s_nop 7
	s_cmp_lt_u32 s46, s72
	s_cbranch_scc1 .Lat_nomask_960
	s_sub_u32 s60, s46, s72
	s_lshl_b32 s60, s60, 6
	v_lshl_add_u32 v0, v252, 2, s60
	v_sub_u32_e32 v0, v246, v0
	v_mov_b32_e32 v1, 0xff800000
	v_cmp_gt_i32_e64 s[60:61], 0, v0
	v_cmp_gt_i32_e64 s[62:63], 32, v0
	v_cmp_gt_i32_e64 s[64:65], 1, v0
	v_cmp_gt_i32_e64 s[66:67], 33, v0
	v_cndmask_b32_e64 v96, v96, v1, s[60:61]
	v_cmp_gt_i32_e64 s[60:61], 2, v0
	v_cndmask_b32_e64 v112, v112, v1, s[62:63]
	v_cmp_gt_i32_e64 s[62:63], 34, v0
	v_cndmask_b32_e64 v97, v97, v1, s[64:65]
	v_cmp_gt_i32_e64 s[64:65], 3, v0
	v_cndmask_b32_e64 v113, v113, v1, s[66:67]
	v_cmp_gt_i32_e64 s[66:67], 35, v0
	v_cndmask_b32_e64 v98, v98, v1, s[60:61]
	v_cmp_gt_i32_e64 s[60:61], 8, v0
	v_cndmask_b32_e64 v114, v114, v1, s[62:63]
	v_cmp_gt_i32_e64 s[62:63], 40, v0
	v_cndmask_b32_e64 v99, v99, v1, s[64:65]
	v_cmp_gt_i32_e64 s[64:65], 9, v0
	v_cndmask_b32_e64 v115, v115, v1, s[66:67]
	v_cmp_gt_i32_e64 s[66:67], 41, v0
	v_cndmask_b32_e64 v100, v100, v1, s[60:61]
	v_cmp_gt_i32_e64 s[60:61], 10, v0
	v_cndmask_b32_e64 v116, v116, v1, s[62:63]
	v_cmp_gt_i32_e64 s[62:63], 42, v0
	v_cndmask_b32_e64 v101, v101, v1, s[64:65]
	v_cmp_gt_i32_e64 s[64:65], 11, v0
	v_cndmask_b32_e64 v117, v117, v1, s[66:67]
	v_cmp_gt_i32_e64 s[66:67], 43, v0
	v_cndmask_b32_e64 v102, v102, v1, s[60:61]
	v_cmp_gt_i32_e64 s[60:61], 16, v0
	v_cndmask_b32_e64 v118, v118, v1, s[62:63]
	v_cmp_gt_i32_e64 s[62:63], 48, v0
	v_cndmask_b32_e64 v103, v103, v1, s[64:65]
	v_cmp_gt_i32_e64 s[64:65], 17, v0
	v_cndmask_b32_e64 v119, v119, v1, s[66:67]
	v_cmp_gt_i32_e64 s[66:67], 49, v0
	v_cndmask_b32_e64 v104, v104, v1, s[60:61]
	v_cmp_gt_i32_e64 s[60:61], 18, v0
	v_cndmask_b32_e64 v120, v120, v1, s[62:63]
	v_cmp_gt_i32_e64 s[62:63], 50, v0
	v_cndmask_b32_e64 v105, v105, v1, s[64:65]
	v_cmp_gt_i32_e64 s[64:65], 19, v0
	v_cndmask_b32_e64 v121, v121, v1, s[66:67]
	v_cmp_gt_i32_e64 s[66:67], 51, v0
	v_cndmask_b32_e64 v106, v106, v1, s[60:61]
	v_cmp_gt_i32_e64 s[60:61], 24, v0
	v_cndmask_b32_e64 v122, v122, v1, s[62:63]
	v_cmp_gt_i32_e64 s[62:63], 56, v0
	v_cndmask_b32_e64 v107, v107, v1, s[64:65]
	v_cmp_gt_i32_e64 s[64:65], 25, v0
	v_cndmask_b32_e64 v123, v123, v1, s[66:67]
	v_cmp_gt_i32_e64 s[66:67], 57, v0
	v_cndmask_b32_e64 v108, v108, v1, s[60:61]
	v_cmp_gt_i32_e64 s[60:61], 26, v0
	v_cndmask_b32_e64 v124, v124, v1, s[62:63]
	v_cmp_gt_i32_e64 s[62:63], 58, v0
	v_cndmask_b32_e64 v109, v109, v1, s[64:65]
	v_cmp_gt_i32_e64 s[64:65], 27, v0
	v_cndmask_b32_e64 v125, v125, v1, s[66:67]
	v_cmp_gt_i32_e64 s[66:67], 59, v0
	v_cndmask_b32_e64 v110, v110, v1, s[60:61]
	s_nop 1
	v_cndmask_b32_e64 v126, v126, v1, s[62:63]
	v_cndmask_b32_e64 v111, v111, v1, s[64:65]
	v_cndmask_b32_e64 v127, v127, v1, s[66:67]
.Lat_nomask_960:
	v_max3_f32 v2, v96, v97, v112
	v_max3_f32 v3, v98, v99, v113
	v_max3_f32 v2, v2, v114, v115
	v_max3_f32 v2, v2, v100, v101
	v_max3_f32 v3, v3, v102, v103
	v_max3_f32 v2, v2, v116, v117
	v_max3_f32 v3, v3, v118, v119
	v_max3_f32 v2, v2, v104, v105
	v_max3_f32 v3, v3, v106, v107
	v_max3_f32 v2, v2, v120, v121
	v_max3_f32 v3, v3, v122, v123
	v_max3_f32 v2, v2, v108, v109
	v_max3_f32 v3, v3, v110, v111
	v_max3_f32 v2, v2, v124, v125
	v_max3_f32 v3, v3, v126, v127
	v_max_f32_e32 v2, v2, v3
	v_mov_b32_e32 v3, v2
	s_nop 1
	v_permlane32_swap_b32_e32 v2, v3
	v_max_f32_e32 v2, v2, v3
	v_mov_b32_e32 v5, 0x41400000
	v_cmp_gt_f32_e32 vcc, v2, v5
	s_mov_b64 s[68:69], vcc
	s_cmp_lg_u64 vcc, 0
	s_cbranch_scc0 .Lat_noresc_960
	v_max_f32_e32 v4, 0, v2
	v_add_f32_e32 v248, v248, v4
	v_sub_f32_e32 v96, v96, v4
	v_sub_f32_e32 v97, v97, v4
	v_sub_f32_e32 v98, v98, v4
	v_sub_f32_e32 v99, v99, v4
	v_sub_f32_e32 v100, v100, v4
	v_sub_f32_e32 v101, v101, v4
	v_sub_f32_e32 v102, v102, v4
	v_sub_f32_e32 v103, v103, v4
	v_sub_f32_e32 v104, v104, v4
	v_sub_f32_e32 v105, v105, v4
	v_sub_f32_e32 v106, v106, v4
	v_sub_f32_e32 v107, v107, v4
	v_sub_f32_e32 v108, v108, v4
	v_sub_f32_e32 v109, v109, v4
	v_sub_f32_e32 v110, v110, v4
	v_sub_f32_e32 v111, v111, v4
	v_sub_f32_e32 v112, v112, v4
	v_sub_f32_e32 v113, v113, v4
	v_sub_f32_e32 v114, v114, v4
	v_sub_f32_e32 v115, v115, v4
	v_sub_f32_e32 v116, v116, v4
	v_sub_f32_e32 v117, v117, v4
	v_sub_f32_e32 v118, v118, v4
	v_sub_f32_e32 v119, v119, v4
	v_sub_f32_e32 v120, v120, v4
	v_sub_f32_e32 v121, v121, v4
	v_sub_f32_e32 v122, v122, v4
	v_sub_f32_e32 v123, v123, v4
	v_sub_f32_e32 v124, v124, v4
	v_sub_f32_e32 v125, v125, v4
	v_sub_f32_e32 v126, v126, v4
	v_sub_f32_e32 v127, v127, v4
	v_xor_b32_e32 v5, 0x80000000, v248
	v_mov_b32_e32 v160, v5
	v_mov_b32_e32 v161, v5
	v_mov_b32_e32 v162, v5
	v_mov_b32_e32 v163, v5
	v_mov_b32_e32 v164, v5
	v_mov_b32_e32 v165, v5
	v_mov_b32_e32 v166, v5
	v_mov_b32_e32 v167, v5
	v_mov_b32_e32 v168, v5
	v_mov_b32_e32 v169, v5
	v_mov_b32_e32 v170, v5
	v_mov_b32_e32 v171, v5
	v_mov_b32_e32 v172, v5
	v_mov_b32_e32 v173, v5
	v_mov_b32_e32 v174, v5
	v_mov_b32_e32 v175, v5
	v_xor_b32_e32 v6, 0x80000000, v4
	v_exp_f32_e32 v6, v6
	s_nop 0
	v_mul_f32_e32 v247, v247, v6
	v_and_b32_e32 v7, 31, v237
	v_lshl_add_u32 v7, v7, 2, v249
	v_cmp_eq_u32_e32 vcc, 0, v252
	s_and_saveexec_b64 s[60:61], vcc
	ds_write_b32 v7, v6
	s_or_b64 exec, exec, s[60:61]
.Lat_noresc_960:
	ds_read_b64_tr_b16 v[200:201], v250 offset:8192
	ds_read_b64_tr_b16 v[202:203], v250 offset:8704
	s_waitcnt lgkmcnt(4)
	v_mfma_f32_32x32x16_bf16 v[32:47], v[176:179], v[192:195], v[32:47]
	v_exp_f32_e32 v96, v96
	v_exp_f32_e32 v97, v97
	ds_read_b64_tr_b16 v[204:205], v250 offset:12288
	ds_read_b64_tr_b16 v[206:207], v250 offset:12800
	s_waitcnt lgkmcnt(4)
	v_mfma_f32_32x32x16_bf16 v[48:63], v[176:179], v[196:199], v[48:63]
	v_exp_f32_e32 v98, v98
	v_exp_f32_e32 v99, v99
	ds_read_b64_tr_b16 v[192:193], v250 offset:1024
	ds_read_b64_tr_b16 v[194:195], v250 offset:1536
	s_waitcnt lgkmcnt(4)
	v_mfma_f32_32x32x16_bf16 v[64:79], v[176:179], v[200:203], v[64:79]
	v_exp_f32_e32 v100, v100
	v_exp_f32_e32 v101, v101
	ds_read_b64_tr_b16 v[196:197], v250 offset:5120
	ds_read_b64_tr_b16 v[198:199], v250 offset:5632
	s_waitcnt lgkmcnt(4)
	v_mfma_f32_32x32x16_bf16 v[80:95], v[176:179], v[204:207], v[80:95]
	v_exp_f32_e32 v102, v102
	v_exp_f32_e32 v103, v103
	v_add_u32_e32 v3, s58, v244
	ds_read_b64_tr_b16 v[200:201], v250 offset:9216
	ds_read_b64_tr_b16 v[202:203], v250 offset:9728
	s_waitcnt lgkmcnt(4)
	v_mfma_f32_32x32x16_bf16 v[32:47], v[180:183], v[192:195], v[32:47]
	v_exp_f32_e32 v104, v104
	v_exp_f32_e32 v105, v105
	ds_read_b128 v[208:211], v3
	ds_read_b64_tr_b16 v[204:205], v250 offset:13312
	ds_read_b64_tr_b16 v[206:207], v250 offset:13824
	s_waitcnt lgkmcnt(5)
	v_mfma_f32_32x32x16_bf16 v[48:63], v[180:183], v[196:199], v[48:63]
	v_exp_f32_e32 v106, v106
	v_exp_f32_e32 v107, v107
	ds_read_b128 v[212:215], v3 offset:512
	ds_read_b64_tr_b16 v[192:193], v250 offset:2048
	ds_read_b64_tr_b16 v[194:195], v250 offset:2560
	s_waitcnt lgkmcnt(6)
	v_mfma_f32_32x32x16_bf16 v[64:79], v[180:183], v[200:203], v[64:79]
	v_exp_f32_e32 v108, v108
	v_exp_f32_e32 v109, v109
	ds_read_b128 v[216:219], v3 offset:2048
	ds_read_b64_tr_b16 v[196:197], v250 offset:6144
	ds_read_b64_tr_b16 v[198:199], v250 offset:6656
	s_waitcnt lgkmcnt(6)
	v_mfma_f32_32x32x16_bf16 v[80:95], v[180:183], v[204:207], v[80:95]
	v_exp_f32_e32 v110, v110
	v_exp_f32_e32 v111, v111
	ds_read_b128 v[220:223], v3 offset:2560
	ds_read_b64_tr_b16 v[200:201], v250 offset:10240
	ds_read_b64_tr_b16 v[202:203], v250 offset:10752
	s_waitcnt lgkmcnt(6)
	v_mfma_f32_32x32x16_bf16 v[32:47], v[184:187], v[192:195], v[32:47]
	v_exp_f32_e32 v112, v112
	v_exp_f32_e32 v113, v113
	ds_read_b128 v[224:227], v3 offset:4096
	ds_read_b64_tr_b16 v[204:205], v250 offset:14336
	ds_read_b64_tr_b16 v[206:207], v250 offset:14848
	s_waitcnt lgkmcnt(6)
	v_mfma_f32_32x32x16_bf16 v[48:63], v[184:187], v[196:199], v[48:63]
	v_exp_f32_e32 v114, v114
	v_exp_f32_e32 v115, v115
	ds_read_b128 v[228:231], v3 offset:4608
	ds_read_b64_tr_b16 v[192:193], v250 offset:3072
	ds_read_b64_tr_b16 v[194:195], v250 offset:3584
	s_waitcnt lgkmcnt(6)
	v_mfma_f32_32x32x16_bf16 v[64:79], v[184:187], v[200:203], v[64:79]
	v_exp_f32_e32 v116, v116
	v_exp_f32_e32 v117, v117
	ds_read_b128 v[232:235], v3 offset:6144
	ds_read_b64_tr_b16 v[196:197], v250 offset:7168
	ds_read_b64_tr_b16 v[198:199], v250 offset:7680
	s_waitcnt lgkmcnt(6)
	v_mfma_f32_32x32x16_bf16 v[80:95], v[184:187], v[204:207], v[80:95]
	v_exp_f32_e32 v118, v118
	v_exp_f32_e32 v119, v119
	ds_read_b128 v[240:243], v3 offset:6656
	ds_read_b64_tr_b16 v[200:201], v250 offset:11264
	ds_read_b64_tr_b16 v[202:203], v250 offset:11776
	s_waitcnt lgkmcnt(6)
	v_mfma_f32_32x32x16_bf16 v[32:47], v[188:191], v[192:195], v[32:47]
	v_exp_f32_e32 v120, v120
	v_exp_f32_e32 v121, v121
	ds_read_b64_tr_b16 v[204:205], v250 offset:15360
	ds_read_b64_tr_b16 v[206:207], v250 offset:15872
	s_waitcnt lgkmcnt(5)
	v_mfma_f32_32x32x16_bf16 v[48:63], v[188:191], v[196:199], v[48:63]
	v_exp_f32_e32 v122, v122
	v_exp_f32_e32 v123, v123
	s_waitcnt lgkmcnt(2)
	v_mfma_f32_32x32x16_bf16 v[64:79], v[188:191], v[200:203], v[64:79]
	v_exp_f32_e32 v124, v124
	v_exp_f32_e32 v125, v125
	s_waitcnt lgkmcnt(0)
	v_mfma_f32_32x32x16_bf16 v[80:95], v[188:191], v[204:207], v[80:95]
	v_exp_f32_e32 v126, v126
	v_exp_f32_e32 v127, v127
	s_waitcnt vmcnt(3) lgkmcnt(0)
	s_barrier
	s_cmp_lg_u64 s[68:69], 0
	s_cbranch_scc0 .Lat_norescO_876
	v_lshl_add_u32 v250, v252, 4, v249
	ds_read_b128 v[0:3], v250 offset:0
	ds_read_b128 v[4:7], v250 offset:32
	ds_read_b128 v[8:11], v250 offset:64
	ds_read_b128 v[12:15], v250 offset:96
	s_nop 7
	s_nop 7
	s_waitcnt lgkmcnt(0)
	v_mul_f32_e32 v32, v32, v0
	v_mul_f32_e32 v33, v33, v1
	v_mul_f32_e32 v34, v34, v2
	v_mul_f32_e32 v35, v35, v3
	v_mul_f32_e32 v36, v36, v4
	v_mul_f32_e32 v37, v37, v5
	v_mul_f32_e32 v38, v38, v6
	v_mul_f32_e32 v39, v39, v7
	v_mul_f32_e32 v40, v40, v8
	v_mul_f32_e32 v41, v41, v9
	v_mul_f32_e32 v42, v42, v10
	v_mul_f32_e32 v43, v43, v11
	v_mul_f32_e32 v44, v44, v12
	v_mul_f32_e32 v45, v45, v13
	v_mul_f32_e32 v46, v46, v14
	v_mul_f32_e32 v47, v47, v15
	v_mul_f32_e32 v48, v48, v0
	v_mul_f32_e32 v49, v49, v1
	v_mul_f32_e32 v50, v50, v2
	v_mul_f32_e32 v51, v51, v3
	v_mul_f32_e32 v52, v52, v4
	v_mul_f32_e32 v53, v53, v5
	v_mul_f32_e32 v54, v54, v6
	v_mul_f32_e32 v55, v55, v7
	v_mul_f32_e32 v56, v56, v8
	v_mul_f32_e32 v57, v57, v9
	v_mul_f32_e32 v58, v58, v10
	v_mul_f32_e32 v59, v59, v11
	v_mul_f32_e32 v60, v60, v12
	v_mul_f32_e32 v61, v61, v13
	v_mul_f32_e32 v62, v62, v14
	v_mul_f32_e32 v63, v63, v15
	v_mul_f32_e32 v64, v64, v0
	v_mul_f32_e32 v65, v65, v1
	v_mul_f32_e32 v66, v66, v2
	v_mul_f32_e32 v67, v67, v3
	v_mul_f32_e32 v68, v68, v4
	v_mul_f32_e32 v69, v69, v5
	v_mul_f32_e32 v70, v70, v6
	v_mul_f32_e32 v71, v71, v7
	v_mul_f32_e32 v72, v72, v8
	v_mul_f32_e32 v73, v73, v9
	v_mul_f32_e32 v74, v74, v10
	v_mul_f32_e32 v75, v75, v11
	v_mul_f32_e32 v76, v76, v12
	v_mul_f32_e32 v77, v77, v13
	v_mul_f32_e32 v78, v78, v14
	v_mul_f32_e32 v79, v79, v15
	v_mul_f32_e32 v80, v80, v0
	v_mul_f32_e32 v81, v81, v1
	v_mul_f32_e32 v82, v82, v2
	v_mul_f32_e32 v83, v83, v3
	v_mul_f32_e32 v84, v84, v4
	v_mul_f32_e32 v85, v85, v5
	v_mul_f32_e32 v86, v86, v6
	v_mul_f32_e32 v87, v87, v7
	v_mul_f32_e32 v88, v88, v8
	v_mul_f32_e32 v89, v89, v9
	v_mul_f32_e32 v90, v90, v10
	v_mul_f32_e32 v91, v91, v11
	v_mul_f32_e32 v92, v92, v12
	v_mul_f32_e32 v93, v93, v13
	v_mul_f32_e32 v94, v94, v14
	v_mul_f32_e32 v95, v95, v15
.Lat_norescO_876:
	s_mov_b32 s67, s56
	s_mov_b32 s56, s57
	s_mov_b32 s57, s58
	s_mov_b32 s58, s67
	s_add_u32 s46, s46, 1
	s_cmp_lt_u32 s46, s45
	s_cbranch_scc1 .Lat_loop
.Lat_drain:
	v_mov_b32_e32 v251, 0
	v_add_f32_e32 v251, v251, v128
	v_add_f32_e32 v251, v251, v129
	v_add_f32_e32 v251, v251, v130
	v_add_f32_e32 v251, v251, v131
	v_cvt_pk_bf16_f32 v176, v128, v129
	v_cvt_pk_bf16_f32 v177, v130, v131
	v_add_f32_e32 v251, v251, v132
	v_add_f32_e32 v251, v251, v133
	v_add_f32_e32 v251, v251, v134
	v_add_f32_e32 v251, v251, v135
	v_cvt_pk_bf16_f32 v178, v132, v133
	v_cvt_pk_bf16_f32 v179, v134, v135
	v_add_f32_e32 v251, v251, v136
	v_add_f32_e32 v251, v251, v137
	v_add_f32_e32 v251, v251, v138
	v_add_f32_e32 v251, v251, v139
	v_cvt_pk_bf16_f32 v180, v136, v137
	v_cvt_pk_bf16_f32 v181, v138, v139
	v_add_f32_e32 v251, v251, v140
	v_add_f32_e32 v251, v251, v141
	v_add_f32_e32 v251, v251, v142
	v_add_f32_e32 v251, v251, v143
	v_cvt_pk_bf16_f32 v182, v140, v141
	v_cvt_pk_bf16_f32 v183, v142, v143
	v_add_f32_e32 v251, v251, v144
	v_add_f32_e32 v251, v251, v145
	v_add_f32_e32 v251, v251, v146
	v_add_f32_e32 v251, v251, v147
	v_cvt_pk_bf16_f32 v184, v144, v145
	v_cvt_pk_bf16_f32 v185, v146, v147
	v_add_f32_e32 v251, v251, v148
	v_add_f32_e32 v251, v251, v149
	v_add_f32_e32 v251, v251, v150
	v_add_f32_e32 v251, v251, v151
	v_cvt_pk_bf16_f32 v186, v148, v149
	v_cvt_pk_bf16_f32 v187, v150, v151
	v_add_f32_e32 v251, v251, v152
	v_add_f32_e32 v251, v251, v153
	v_add_f32_e32 v251, v251, v154
	v_add_f32_e32 v251, v251, v155
	v_cvt_pk_bf16_f32 v188, v152, v153
	v_cvt_pk_bf16_f32 v189, v154, v155
	v_add_f32_e32 v251, v251, v156
	v_add_f32_e32 v251, v251, v157
	v_add_f32_e32 v251, v251, v158
	v_add_f32_e32 v251, v251, v159
	v_cvt_pk_bf16_f32 v190, v156, v157
	v_cvt_pk_bf16_f32 v191, v158, v159
	v_add_f32_e32 v247, v247, v251
	s_lshl_b32 s60, s56, 1
	v_add_u32_e32 v250, s60, v245
	ds_read_b64_tr_b16 v[192:193], v250 offset:0
	ds_read_b64_tr_b16 v[194:195], v250 offset:512
	s_waitcnt lgkmcnt(0)
	v_mfma_f32_32x32x16_bf16 v[32:47], v[176:179], v[192:195], v[32:47]
	ds_read_b64_tr_b16 v[196:197], v250 offset:4096
	ds_read_b64_tr_b16 v[198:199], v250 offset:4608
	s_waitcnt lgkmcnt(0)
	v_mfma_f32_32x32x16_bf16 v[48:63], v[176:179], v[196:199], v[48:63]
	ds_read_b64_tr_b16 v[200:201], v250 offset:8192
	ds_read_b64_tr_b16 v[202:203], v250 offset:8704
	s_waitcnt lgkmcnt(0)
	v_mfma_f32_32x32x16_bf16 v[64:79], v[176:179], v[200:203], v[64:79]
	ds_read_b64_tr_b16 v[204:205], v250 offset:12288
	ds_read_b64_tr_b16 v[206:207], v250 offset:12800
	s_waitcnt lgkmcnt(0)
	v_mfma_f32_32x32x16_bf16 v[80:95], v[176:179], v[204:207], v[80:95]
	ds_read_b64_tr_b16 v[192:193], v250 offset:1024
	ds_read_b64_tr_b16 v[194:195], v250 offset:1536
	s_waitcnt lgkmcnt(0)
	v_mfma_f32_32x32x16_bf16 v[32:47], v[180:183], v[192:195], v[32:47]
	ds_read_b64_tr_b16 v[196:197], v250 offset:5120
	ds_read_b64_tr_b16 v[198:199], v250 offset:5632
	s_waitcnt lgkmcnt(0)
	v_mfma_f32_32x32x16_bf16 v[48:63], v[180:183], v[196:199], v[48:63]
	ds_read_b64_tr_b16 v[200:201], v250 offset:9216
	ds_read_b64_tr_b16 v[202:203], v250 offset:9728
	s_waitcnt lgkmcnt(0)
	v_mfma_f32_32x32x16_bf16 v[64:79], v[180:183], v[200:203], v[64:79]
	ds_read_b64_tr_b16 v[204:205], v250 offset:13312
	ds_read_b64_tr_b16 v[206:207], v250 offset:13824
	s_waitcnt lgkmcnt(0)
	v_mfma_f32_32x32x16_bf16 v[80:95], v[180:183], v[204:207], v[80:95]
	ds_read_b64_tr_b16 v[192:193], v250 offset:2048
	ds_read_b64_tr_b16 v[194:195], v250 offset:2560
	s_waitcnt lgkmcnt(0)
	v_mfma_f32_32x32x16_bf16 v[32:47], v[184:187], v[192:195], v[32:47]
	ds_read_b64_tr_b16 v[196:197], v250 offset:6144
	ds_read_b64_tr_b16 v[198:199], v250 offset:6656
	s_waitcnt lgkmcnt(0)
	v_mfma_f32_32x32x16_bf16 v[48:63], v[184:187], v[196:199], v[48:63]
	ds_read_b64_tr_b16 v[200:201], v250 offset:10240
	ds_read_b64_tr_b16 v[202:203], v250 offset:10752
	s_waitcnt lgkmcnt(0)
	v_mfma_f32_32x32x16_bf16 v[64:79], v[184:187], v[200:203], v[64:79]
	ds_read_b64_tr_b16 v[204:205], v250 offset:14336
	ds_read_b64_tr_b16 v[206:207], v250 offset:14848
	s_waitcnt lgkmcnt(0)
	v_mfma_f32_32x32x16_bf16 v[80:95], v[184:187], v[204:207], v[80:95]
	ds_read_b64_tr_b16 v[192:193], v250 offset:3072
	ds_read_b64_tr_b16 v[194:195], v250 offset:3584
	s_waitcnt lgkmcnt(0)
	v_mfma_f32_32x32x16_bf16 v[32:47], v[188:191], v[192:195], v[32:47]
	ds_read_b64_tr_b16 v[196:197], v250 offset:7168
	ds_read_b64_tr_b16 v[198:199], v250 offset:7680
	s_waitcnt lgkmcnt(0)
	v_mfma_f32_32x32x16_bf16 v[48:63], v[188:191], v[196:199], v[48:63]
	ds_read_b64_tr_b16 v[200:201], v250 offset:11264
	ds_read_b64_tr_b16 v[202:203], v250 offset:11776
	s_waitcnt lgkmcnt(0)
	v_mfma_f32_32x32x16_bf16 v[64:79], v[188:191], v[200:203], v[64:79]
	ds_read_b64_tr_b16 v[204:205], v250 offset:15360
	ds_read_b64_tr_b16 v[206:207], v250 offset:15872
	s_waitcnt lgkmcnt(0)
	v_mfma_f32_32x32x16_bf16 v[80:95], v[188:191], v[204:207], v[80:95]
	v_mov_b32_e32 v250, v247
	v_mov_b32_e32 v251, v247
	s_nop 1
	v_permlane32_swap_b32_e32 v250, v251
	v_add_f32_e32 v250, v250, v251
	s_waitcnt vmcnt(0) lgkmcnt(0)
	s_barrier
	v_and_b32_e32 v244, 31, v237
	v_lshl_add_u32 v244, v244, 2, v249
	v_cmp_eq_u32_e32 vcc, 0, v252
	s_and_saveexec_b64 s[60:61], vcc
	ds_write_b32 v244, v250 offset:128
	s_or_b64 exec, exec, s[60:61]
	s_waitcnt lgkmcnt(0)
	v_lshl_add_u32 v250, v252, 4, v249
	ds_read_b128 v[0:3], v250 offset:128
	ds_read_b128 v[4:7], v250 offset:160
	ds_read_b128 v[8:11], v250 offset:192
	ds_read_b128 v[12:15], v250 offset:224
	s_waitcnt lgkmcnt(0)
	v_rcp_f32_e32 v0, v0
	v_rcp_f32_e32 v1, v1
	v_rcp_f32_e32 v2, v2
	v_rcp_f32_e32 v3, v3
	v_rcp_f32_e32 v4, v4
	v_rcp_f32_e32 v5, v5
	v_rcp_f32_e32 v6, v6
	v_rcp_f32_e32 v7, v7
	v_rcp_f32_e32 v8, v8
	v_rcp_f32_e32 v9, v9
	v_rcp_f32_e32 v10, v10
	v_rcp_f32_e32 v11, v11
	v_rcp_f32_e32 v12, v12
	v_rcp_f32_e32 v13, v13
	v_rcp_f32_e32 v14, v14
	v_rcp_f32_e32 v15, v15
	s_nop 7
	s_nop 7
	s_lshl_b32 s60, s47, 13
	v_and_b32_e32 v250, 31, v237
	v_lshlrev_b32_e32 v250, 1, v250
	v_add_u32_e32 v250, s60, v250
	v_lshlrev_b32_e32 v251, 10, v252
	v_add_u32_e32 v250, v250, v251
	v_mul_f32_e32 v251, v32, v0
	v_cvt_pk_bf16_f32 v251, v251, v251
	ds_write_b16 v250, v251 offset:0
	v_mul_f32_e32 v251, v48, v0
	v_cvt_pk_bf16_f32 v251, v251, v251
	ds_write_b16 v250, v251 offset:64
	v_mul_f32_e32 v251, v64, v0
	v_cvt_pk_bf16_f32 v251, v251, v251
	ds_write_b16 v250, v251 offset:128
	v_mul_f32_e32 v251, v80, v0
	v_cvt_pk_bf16_f32 v251, v251, v251
	ds_write_b16 v250, v251 offset:192
	v_mul_f32_e32 v251, v33, v1
	v_cvt_pk_bf16_f32 v251, v251, v251
	ds_write_b16 v250, v251 offset:256
	v_mul_f32_e32 v251, v49, v1
	v_cvt_pk_bf16_f32 v251, v251, v251
	ds_write_b16 v250, v251 offset:320
	v_mul_f32_e32 v251, v65, v1
	v_cvt_pk_bf16_f32 v251, v251, v251
	ds_write_b16 v250, v251 offset:384
	v_mul_f32_e32 v251, v81, v1
	v_cvt_pk_bf16_f32 v251, v251, v251
	ds_write_b16 v250, v251 offset:448
	v_mul_f32_e32 v251, v34, v2
	v_cvt_pk_bf16_f32 v251, v251, v251
	ds_write_b16 v250, v251 offset:512
	v_mul_f32_e32 v251, v50, v2
	v_cvt_pk_bf16_f32 v251, v251, v251
	ds_write_b16 v250, v251 offset:576
	v_mul_f32_e32 v251, v66, v2
	v_cvt_pk_bf16_f32 v251, v251, v251
	ds_write_b16 v250, v251 offset:640
	v_mul_f32_e32 v251, v82, v2
	v_cvt_pk_bf16_f32 v251, v251, v251
	ds_write_b16 v250, v251 offset:704
	v_mul_f32_e32 v251, v35, v3
	v_cvt_pk_bf16_f32 v251, v251, v251
	ds_write_b16 v250, v251 offset:768
	v_mul_f32_e32 v251, v51, v3
	v_cvt_pk_bf16_f32 v251, v251, v251
	ds_write_b16 v250, v251 offset:832
	v_mul_f32_e32 v251, v67, v3
	v_cvt_pk_bf16_f32 v251, v251, v251
	ds_write_b16 v250, v251 offset:896
	v_mul_f32_e32 v251, v83, v3
	v_cvt_pk_bf16_f32 v251, v251, v251
	ds_write_b16 v250, v251 offset:960
	v_mul_f32_e32 v251, v36, v4
	v_cvt_pk_bf16_f32 v251, v251, v251
	ds_write_b16 v250, v251 offset:2048
	v_mul_f32_e32 v251, v52, v4
	v_cvt_pk_bf16_f32 v251, v251, v251
	ds_write_b16 v250, v251 offset:2112
	v_mul_f32_e32 v251, v68, v4
	v_cvt_pk_bf16_f32 v251, v251, v251
	ds_write_b16 v250, v251 offset:2176
	v_mul_f32_e32 v251, v84, v4
	v_cvt_pk_bf16_f32 v251, v251, v251
	ds_write_b16 v250, v251 offset:2240
	v_mul_f32_e32 v251, v37, v5
	v_cvt_pk_bf16_f32 v251, v251, v251
	ds_write_b16 v250, v251 offset:2304
	v_mul_f32_e32 v251, v53, v5
	v_cvt_pk_bf16_f32 v251, v251, v251
	ds_write_b16 v250, v251 offset:2368
	v_mul_f32_e32 v251, v69, v5
	v_cvt_pk_bf16_f32 v251, v251, v251
	ds_write_b16 v250, v251 offset:2432
	v_mul_f32_e32 v251, v85, v5
	v_cvt_pk_bf16_f32 v251, v251, v251
	ds_write_b16 v250, v251 offset:2496
	v_mul_f32_e32 v251, v38, v6
	v_cvt_pk_bf16_f32 v251, v251, v251
	ds_write_b16 v250, v251 offset:2560
	v_mul_f32_e32 v251, v54, v6
	v_cvt_pk_bf16_f32 v251, v251, v251
	ds_write_b16 v250, v251 offset:2624
	v_mul_f32_e32 v251, v70, v6
	v_cvt_pk_bf16_f32 v251, v251, v251
	ds_write_b16 v250, v251 offset:2688
	v_mul_f32_e32 v251, v86, v6
	v_cvt_pk_bf16_f32 v251, v251, v251
	ds_write_b16 v250, v251 offset:2752
	v_mul_f32_e32 v251, v39, v7
	v_cvt_pk_bf16_f32 v251, v251, v251
	ds_write_b16 v250, v251 offset:2816
	v_mul_f32_e32 v251, v55, v7
	v_cvt_pk_bf16_f32 v251, v251, v251
	ds_write_b16 v250, v251 offset:2880
	v_mul_f32_e32 v251, v71, v7
	v_cvt_pk_bf16_f32 v251, v251, v251
	ds_write_b16 v250, v251 offset:2944
	v_mul_f32_e32 v251, v87, v7
	v_cvt_pk_bf16_f32 v251, v251, v251
	ds_write_b16 v250, v251 offset:3008
	v_mul_f32_e32 v251, v40, v8
	v_cvt_pk_bf16_f32 v251, v251, v251
	ds_write_b16 v250, v251 offset:4096
	v_mul_f32_e32 v251, v56, v8
	v_cvt_pk_bf16_f32 v251, v251, v251
	ds_write_b16 v250, v251 offset:4160
	v_mul_f32_e32 v251, v72, v8
	v_cvt_pk_bf16_f32 v251, v251, v251
	ds_write_b16 v250, v251 offset:4224
	v_mul_f32_e32 v251, v88, v8
	v_cvt_pk_bf16_f32 v251, v251, v251
	ds_write_b16 v250, v251 offset:4288
	v_mul_f32_e32 v251, v41, v9
	v_cvt_pk_bf16_f32 v251, v251, v251
	ds_write_b16 v250, v251 offset:4352
	v_mul_f32_e32 v251, v57, v9
	v_cvt_pk_bf16_f32 v251, v251, v251
	ds_write_b16 v250, v251 offset:4416
	v_mul_f32_e32 v251, v73, v9
	v_cvt_pk_bf16_f32 v251, v251, v251
	ds_write_b16 v250, v251 offset:4480
	v_mul_f32_e32 v251, v89, v9
	v_cvt_pk_bf16_f32 v251, v251, v251
	ds_write_b16 v250, v251 offset:4544
	v_mul_f32_e32 v251, v42, v10
	v_cvt_pk_bf16_f32 v251, v251, v251
	ds_write_b16 v250, v251 offset:4608
	v_mul_f32_e32 v251, v58, v10
	v_cvt_pk_bf16_f32 v251, v251, v251
	ds_write_b16 v250, v251 offset:4672
	v_mul_f32_e32 v251, v74, v10
	v_cvt_pk_bf16_f32 v251, v251, v251
	ds_write_b16 v250, v251 offset:4736
	v_mul_f32_e32 v251, v90, v10
	v_cvt_pk_bf16_f32 v251, v251, v251
	ds_write_b16 v250, v251 offset:4800
	v_mul_f32_e32 v251, v43, v11
	v_cvt_pk_bf16_f32 v251, v251, v251
	ds_write_b16 v250, v251 offset:4864
	v_mul_f32_e32 v251, v59, v11
	v_cvt_pk_bf16_f32 v251, v251, v251
	ds_write_b16 v250, v251 offset:4928
	v_mul_f32_e32 v251, v75, v11
	v_cvt_pk_bf16_f32 v251, v251, v251
	ds_write_b16 v250, v251 offset:4992
	v_mul_f32_e32 v251, v91, v11
	v_cvt_pk_bf16_f32 v251, v251, v251
	ds_write_b16 v250, v251 offset:5056
	v_mul_f32_e32 v251, v44, v12
	v_cvt_pk_bf16_f32 v251, v251, v251
	ds_write_b16 v250, v251 offset:6144
	v_mul_f32_e32 v251, v60, v12
	v_cvt_pk_bf16_f32 v251, v251, v251
	ds_write_b16 v250, v251 offset:6208
	v_mul_f32_e32 v251, v76, v12
	v_cvt_pk_bf16_f32 v251, v251, v251
	ds_write_b16 v250, v251 offset:6272
	v_mul_f32_e32 v251, v92, v12
	v_cvt_pk_bf16_f32 v251, v251, v251
	ds_write_b16 v250, v251 offset:6336
	v_mul_f32_e32 v251, v45, v13
	v_cvt_pk_bf16_f32 v251, v251, v251
	ds_write_b16 v250, v251 offset:6400
	v_mul_f32_e32 v251, v61, v13
	v_cvt_pk_bf16_f32 v251, v251, v251
	ds_write_b16 v250, v251 offset:6464
	v_mul_f32_e32 v251, v77, v13
	v_cvt_pk_bf16_f32 v251, v251, v251
	ds_write_b16 v250, v251 offset:6528
	v_mul_f32_e32 v251, v93, v13
	v_cvt_pk_bf16_f32 v251, v251, v251
	ds_write_b16 v250, v251 offset:6592
	v_mul_f32_e32 v251, v46, v14
	v_cvt_pk_bf16_f32 v251, v251, v251
	ds_write_b16 v250, v251 offset:6656
	v_mul_f32_e32 v251, v62, v14
	v_cvt_pk_bf16_f32 v251, v251, v251
	ds_write_b16 v250, v251 offset:6720
	v_mul_f32_e32 v251, v78, v14
	v_cvt_pk_bf16_f32 v251, v251, v251
	ds_write_b16 v250, v251 offset:6784
	v_mul_f32_e32 v251, v94, v14
	v_cvt_pk_bf16_f32 v251, v251, v251
	ds_write_b16 v250, v251 offset:6848
	v_mul_f32_e32 v251, v47, v15
	v_cvt_pk_bf16_f32 v251, v251, v251
	ds_write_b16 v250, v251 offset:6912
	v_mul_f32_e32 v251, v63, v15
	v_cvt_pk_bf16_f32 v251, v251, v251
	ds_write_b16 v250, v251 offset:6976
	v_mul_f32_e32 v251, v79, v15
	v_cvt_pk_bf16_f32 v251, v251, v251
	ds_write_b16 v250, v251 offset:7040
	v_mul_f32_e32 v251, v95, v15
	v_cvt_pk_bf16_f32 v251, v251, v251
	ds_write_b16 v250, v251 offset:7104
	s_waitcnt lgkmcnt(0)
	v_lshrrev_b32_e32 v251, 4, v237
	v_and_b32_e32 v244, 15, v237
	v_lshlrev_b32_e32 v245, 8, v251
	v_lshl_or_b32 v245, v244, 4, v245
	v_add_u32_e32 v245, s60, v245
	v_lshlrev_b32_e32 v246, 11, v251
	v_lshl_or_b32 v246, v244, 4, v246
	ds_read_b128 v[16:19], v245 offset:0
	s_waitcnt lgkmcnt(0)
	global_store_dwordx4 v246, v[16:19], s[52:53]
	v_add_u32_e32 v246, 0x2000, v246
	s_nop 1
	ds_read_b128 v[16:19], v245 offset:1024
	s_waitcnt lgkmcnt(0)
	global_store_dwordx4 v246, v[16:19], s[52:53]
	v_add_u32_e32 v246, 0x2000, v246
	s_nop 1
	ds_read_b128 v[16:19], v245 offset:2048
	s_waitcnt lgkmcnt(0)
	global_store_dwordx4 v246, v[16:19], s[52:53]
	v_add_u32_e32 v246, 0x2000, v246
	s_nop 1
	ds_read_b128 v[16:19], v245 offset:3072
	s_waitcnt lgkmcnt(0)
	global_store_dwordx4 v246, v[16:19], s[52:53]
	v_add_u32_e32 v246, 0x2000, v246
	s_nop 1
	ds_read_b128 v[16:19], v245 offset:4096
	s_waitcnt lgkmcnt(0)
	global_store_dwordx4 v246, v[16:19], s[52:53]
	v_add_u32_e32 v246, 0x2000, v246
	s_nop 1
	ds_read_b128 v[16:19], v245 offset:5120
	s_waitcnt lgkmcnt(0)
	global_store_dwordx4 v246, v[16:19], s[52:53]
	v_add_u32_e32 v246, 0x2000, v246
	s_nop 1
	ds_read_b128 v[16:19], v245 offset:6144
	s_waitcnt lgkmcnt(0)
	global_store_dwordx4 v246, v[16:19], s[52:53]
	v_add_u32_e32 v246, 0x2000, v246
	s_nop 1
	ds_read_b128 v[16:19], v245 offset:7168
	s_waitcnt lgkmcnt(0)
	global_store_dwordx4 v246, v[16:19], s[52:53]
	v_add_u32_e32 v246, 0x2000, v246
	s_nop 1
	s_waitcnt lgkmcnt(0)
	s_barrier
.Lat_unit_end:
	s_and_saveexec_b64 s[4:5], s[0:1]
	s_cbranch_execz .LBB0_770
	v_cmp_lt_u32_e32 vcc, s43, v253
	s_and_saveexec_b64 s[6:7], vcc
	s_xor_b64 s[6:7], exec, s[6:7]
	s_cbranch_execz .LBB0_837
	s_add_i32 s8, s44, 1
	s_lshl_b32 s2, s8, 8
	s_and_b32 s2, s2, 0x700
	s_add_i32 s30, s44, 2
	v_mov_b32_e32 v0, s2
	s_lshl_b32 s2, s30, 8
	s_and_b32 s2, s2, 0x700
	s_add_i32 s29, s44, 3
	global_load_dword v5, v0, s[82:83] sc1
	v_mov_b32_e32 v0, s2
	s_lshl_b32 s2, s29, 8
	s_and_b32 s2, s2, 0x700
	s_add_i32 s28, s44, 4
	global_load_dword v7, v0, s[82:83] sc1
	v_mov_b32_e32 v0, s2
	s_lshl_b32 s2, s28, 8
	s_and_b32 s2, s2, 0x700
	s_add_i32 s10, s44, 5
	global_load_dword v6, v0, s[82:83] sc1
	v_mov_b32_e32 v0, s2
	s_lshl_b32 s2, s10, 8
	s_and_b32 s2, s2, 0x700
	global_load_dword v4, v0, s[82:83] sc1
	v_mov_b32_e32 v0, s2
	s_add_i32 s2, s44, 6
	s_lshl_b32 s9, s2, 8
	s_and_b32 s9, s9, 0x700
	s_add_i32 s44, s44, 7
	global_load_dword v3, v0, s[82:83] sc1
	v_mov_b32_e32 v0, s9
	s_lshl_b32 s9, s44, 8
	s_and_b32 s9, s9, 0x700
	global_load_dword v2, v0, s[82:83] sc1
	v_mov_b32_e32 v0, s9
	global_load_dword v0, v0, s[82:83] sc1
	s_waitcnt vmcnt(6)
	v_cmp_gt_u32_e32 vcc, s41, v5
	v_mov_b32_e32 v5, -1
	s_cbranch_vccz .LBB0_806
	s_mov_b64 s[24:25], exec
	v_mbcnt_lo_u32_b32 v5, s24, 0
	v_mbcnt_hi_u32_b32 v5, s25, v5
	s_and_b32 s26, s8, 7
	v_cmp_eq_u32_e32 vcc, 0, v5
	s_and_saveexec_b64 s[8:9], vcc
	s_cbranch_execz .LBB0_805
	s_lshl_b32 s27, s26, 8
	s_bcnt1_i32_b64 s24, s[24:25]
	v_mov_b32_e32 v8, s27
	v_mov_b32_e32 v9, s24
	global_atomic_add v8, v8, v9, s[82:83] sc0

.LBB0_837:
	s_andn2_saveexec_b64 s[6:7], s[6:7]
	s_cbranch_execz .LBB0_769
	s_and_b32 s2, s40, 0x7fffff00
	v_or_b32_e32 v5, s2, v253
	s_branch .LBB0_769
